# attention off-diagonal tiles: own copy with K fragments and score accumulators swapped, so the 16 v_mov_b64 score copies before the exponent block are gone
# speedup vs baseline: 1.0181x; 1.0093x over previous
; __device__ __forceinline__ void attn_unit(const Params& P, int li, LAS unsigned char* lds, int b, int h, int qb, float lam, float one_m_li) {
;     ...
;         if (t <= cw) {
;             f32x16 p0, p1;
;             const LAS unsigned char* kp = cb + mp * 8192 + r32 * 128;
;             bf16x8 kf[8];
; #pragma unroll
;             for (int d0 = 0; d0 < 4; ++d0) { kf[2 * d0] = *(const LAS bf16x8*)(kp + coff[d0]); kf[2 * d0 + 1] = *(const LAS bf16x8*)(kp + 4096 + coff[d0]); }
;             const bool diag = (t == cw);
;             if (diag) { p0 = f32x16{}; p1 = f32x16{}; }
;             else {
;                 const float nc0 = -(sl * ((float)((cw - t) * 64) + qinf) + m), nc1 = fadd_s(nc0, sl32);
;                 float b0[4], b1[4];
;                 b0[0] = nc0; b0[1] = fadd_s(nc0, sl8); b0[2] = fma2_s(sl8, nc0); b0[3] = fadd_s(nc0, sl24);
;                 b1[0] = nc1; b1[1] = fadd_s(nc1, sl8); b1[2] = fma2_s(sl8, nc1); b1[3] = fadd_s(nc1, sl24);
; #pragma unroll
;                 for (int q = 0; q < 4; ++q) {
;                     p0[4 * q] = b0[q]; p0[4 * q + 1] = fadd_s(b0[q], sl); p0[4 * q + 2] = fma2_s(sl, b0[q]); p0[4 * q + 3] = fadd_s(b0[q], sl3);
;                     p1[4 * q] = b1[q]; p1[4 * q + 1] = fadd_s(b1[q], sl); p1[4 * q + 2] = fma2_s(sl, b1[q]); p1[4 * q + 3] = fadd_s(b1[q], sl3);
;                 }
;             }
;             __builtin_amdgcn_sched_barrier(0);
;             __builtin_amdgcn_s_setprio(1);
; #pragma unroll
;             for (int d0 = 0; d0 < 4; ++d0) {
;                 p0 = __builtin_amdgcn_mfma_f32_32x32x16_bf16(kf[2 * d0], qr[d0], p0, 0, 0, 0);
;                 p1 = __builtin_amdgcn_mfma_f32_32x32x16_bf16(kf[2 * d0 + 1], qr[d0], p1, 0, 0, 0);
;             }
;             __builtin_amdgcn_s_setprio(0);
;             if (diag) {
;                 float qf = qinf; asm volatile("" : "+v"(qf));
; #pragma unroll
;                 for (int r = 0; r < 16; ++r) { const float d0 = qf - (float)crow(r, 0);
;                     p0[r] = fmaf(-sl, fabsf(d0), p0[r]); p1[r] = fmaf(-sl, fabsf(d0 - 32.f), p1[r]); }
;             }
;             float mx = max3f(p0[0], p1[0], p0[1]);
; #pragma unroll
;             for (int r = 1; r < 15; ++r) mx = max3f(mx, p1[r], p0[r + 1]);
;             mx = max3f(mx, p1[15], mx);
;             const float mt = xor32_max(mx);
;             bool resc; float ra;
;             if (diag) {
.Lattn_offdiag:
	s_lshl_b32 s10, s21, 15
	s_and_b32 s22, s10, 0x18000
	v_add_u32_e32 v112, s22, v227
	v_add_u32_e32 v113, v112, v225
	ds_read_b128 v[76:79], v113
	ds_read_b128 v[68:71], v113 offset:4096
	v_add_u32_e32 v113, v112, v224
	ds_read_b128 v[72:75], v113
	ds_read_b128 v[92:95], v113 offset:4096
	v_add_u32_e32 v113, v112, v223
	v_add_u32_e32 v112, v112, v221
	ds_read_b128 v[64:67], v113
	ds_read_b128 v[84:87], v113 offset:4096
	ds_read_b128 v[88:91], v112
	ds_read_b128 v[80:83], v112 offset:4096
	s_sub_i32 s4, s31, s4
	s_lshl_b32 s4, s4, 6
	v_cvt_f32_i32_e32 v112, s4
	v_add_f32_e32 v112, v220, v112
	v_fma_f32 v112, v197, v112, v232
	v_xor_b32_e32 v96, 0x80000000, v112
	v_add_f32_e32 v112, v96, v201
	v_add_f32_e32 v100, v96, v199
	v_fma_f32 v104, v199, 2.0, v96
	v_add_f32_e32 v108, v96, v200
	v_add_f32_e32 v97, v96, v197
	v_fma_f32 v98, v197, 2.0, v96
	s_nop 0
	v_add_f32_e32 v116, v112, v199
	v_fma_f32 v120, v199, 2.0, v112
	v_add_f32_e32 v124, v112, v200
	v_add_f32_e32 v99, v96, v198
	v_add_f32_e32 v113, v112, v197
	v_fma_f32 v114, v197, 2.0, v112
	v_add_f32_e32 v115, v112, v198
	v_add_f32_e32 v101, v100, v197
	v_fma_f32 v102, v197, 2.0, v100
	v_add_f32_e32 v103, v100, v198
	s_nop 0
	v_add_f32_e32 v117, v116, v197
	v_fma_f32 v118, v197, 2.0, v116
	v_add_f32_e32 v119, v116, v198
	v_add_f32_e32 v105, v104, v197
	v_fma_f32 v106, v197, 2.0, v104
	v_add_f32_e32 v107, v104, v198
	v_add_f32_e32 v121, v120, v197
	v_fma_f32 v122, v197, 2.0, v120
	v_add_f32_e32 v123, v120, v198
	v_add_f32_e32 v109, v108, v197
	v_fma_f32 v110, v197, 2.0, v108
	v_add_f32_e32 v111, v108, v198
	v_add_f32_e32 v125, v124, v197
	v_fma_f32 v126, v197, 2.0, v124
	v_add_f32_e32 v127, v124, v198
	s_setprio 1
	s_waitcnt lgkmcnt(0)
	v_mfma_f32_32x32x16_bf16 v[96:111], v[76:79], v[128:131], v[96:111]
	v_mfma_f32_32x32x16_bf16 v[112:127], v[68:71], v[128:131], v[112:127]
	v_mfma_f32_32x32x16_bf16 v[96:111], v[72:75], v[132:135], v[96:111]
	v_mfma_f32_32x32x16_bf16 v[112:127], v[92:95], v[132:135], v[112:127]
	v_mfma_f32_32x32x16_bf16 v[96:111], v[64:67], v[136:139], v[96:111]
	v_mfma_f32_32x32x16_bf16 v[112:127], v[84:87], v[136:139], v[112:127]
	v_mfma_f32_32x32x16_bf16 v[96:111], v[88:91], v[140:143], v[96:111]
	v_mfma_f32_32x32x16_bf16 v[112:127], v[80:83], v[140:143], v[112:127]
	s_setprio 0
	s_nop 4
	v_max3_f32 v80, v96, v97, v98
	v_max3_f32 v80, v80, v99, v100
	v_max3_f32 v80, v80, v101, v102
	v_max3_f32 v80, v80, v103, v104
	v_max3_f32 v80, v80, v105, v106
	v_max3_f32 v80, v80, v107, v108
	v_max3_f32 v80, v80, v109, v110
	v_max3_f32 v80, v80, v111, v112
	v_max3_f32 v80, v80, v113, v114
	v_max3_f32 v80, v80, v115, v116
	v_max3_f32 v80, v80, v117, v118
	v_max3_f32 v80, v80, v119, v120
	v_max3_f32 v80, v80, v121, v122
	v_max3_f32 v80, v80, v123, v124
	v_max3_f32 v80, v80, v125, v126
	v_max3_f32 v80, v80, v127, v80
	s_nop 0
	v_mov_b32_e32 v81, v80
	s_nop 1
	v_permlane32_swap_b32_e32 v80, v81
	v_max_f32_e32 v81, v81, v81
	v_max_f32_e32 v80, v80, v80
	v_max_f32_e32 v233, v80, v81
	s_mov_b32 s4, 0x41000000
	v_cmp_lt_f32_e32 vcc, s4, v233
	s_mov_b64 s[22:23], 0
	s_cbranch_vccz .Lattn_od_keep
	v_max_f32_e32 v80, v233, v233
	v_max_f32_e32 v164, 0, v80
	v_exp_f32_e64 v192, -v164
	v_sub_f32_e32 v111, v111, v164
	v_sub_f32_e32 v110, v110, v164
	v_sub_f32_e32 v109, v109, v164
	v_sub_f32_e32 v108, v108, v164
	v_sub_f32_e32 v107, v107, v164
	v_sub_f32_e32 v106, v106, v164
	v_sub_f32_e32 v105, v105, v164
	v_sub_f32_e32 v104, v104, v164
	v_sub_f32_e32 v103, v103, v164
	v_sub_f32_e32 v102, v102, v164
	v_sub_f32_e32 v101, v101, v164
	v_sub_f32_e32 v100, v100, v164
	v_sub_f32_e32 v99, v99, v164
	v_sub_f32_e32 v98, v98, v164
	v_sub_f32_e32 v97, v97, v164
	v_sub_f32_e32 v96, v96, v164
	v_sub_f32_e32 v127, v127, v164
	v_sub_f32_e32 v126, v126, v164
	v_sub_f32_e32 v125, v125, v164
	v_sub_f32_e32 v124, v124, v164
	v_sub_f32_e32 v123, v123, v164
	v_sub_f32_e32 v122, v122, v164
	v_sub_f32_e32 v121, v121, v164
	v_sub_f32_e32 v120, v120, v164
	v_sub_f32_e32 v119, v119, v164
	v_sub_f32_e32 v118, v118, v164
	v_sub_f32_e32 v117, v117, v164
	v_sub_f32_e32 v116, v116, v164
	v_sub_f32_e32 v115, v115, v164
	v_sub_f32_e32 v114, v114, v164
	v_sub_f32_e32 v113, v113, v164
	v_sub_f32_e32 v112, v112, v164
	v_add_f32_e32 v187, v232, v164
	s_mov_b64 s[42:43], -1
	s_branch .LBB0_422
.Lattn_od_keep:
	v_mov_b32_e32 v192, 1.0
	v_mov_b32_e32 v187, v232
	s_mov_b64 s[42:43], 0
	s_branch .LBB0_422

; #define LAS __attribute__((address_space(3)))
; __device__ __forceinline__ float fadd_s(float a, float b) { float r; asm("v_add_f32_e32 %0, %1, %2" : "=v"(r) : "v"(a), "v"(b)); return r; }
; __device__ __forceinline__ float fma2_s(float a, float c) { float r; asm("v_fma_f32 %0, %1, 2.0, %2" : "=v"(r) : "v"(a), "v"(c)); return r; }
; __device__ __forceinline__ void attn_unit(const Params& P, int li, LAS unsigned char* lds, int b, int h, int qb, float lam, float one_m_li) {
;     ...
;         if (t <= cw) {
;             f32x16 p0, p1;
;             const LAS unsigned char* kp = cb + mp * 8192 + r32 * 128;
;             bf16x8 kf[8];
; #pragma unroll
;             for (int d0 = 0; d0 < 4; ++d0) { kf[2 * d0] = *(const LAS bf16x8*)(kp + coff[d0]); kf[2 * d0 + 1] = *(const LAS bf16x8*)(kp + 4096 + coff[d0]); }
;             const bool diag = (t == cw);
;             if (diag) { p0 = f32x16{}; p1 = f32x16{}; }
;             else {
;                 const float nc0 = -(sl * ((float)((cw - t) * 64) + qinf) + m), nc1 = fadd_s(nc0, sl32);
;                 float b0[4], b1[4];
;                 b0[0] = nc0; b0[1] = fadd_s(nc0, sl8); b0[2] = fma2_s(sl8, nc0); b0[3] = fadd_s(nc0, sl24);
;                 b1[0] = nc1; b1[1] = fadd_s(nc1, sl8); b1[2] = fma2_s(sl8, nc1); b1[3] = fadd_s(nc1, sl24);
; #pragma unroll
;                 for (int q = 0; q < 4; ++q) {
;                     p0[4 * q] = b0[q]; p0[4 * q + 1] = fadd_s(b0[q], sl); p0[4 * q + 2] = fma2_s(sl, b0[q]); p0[4 * q + 3] = fadd_s(b0[q], sl3);
;                     p1[4 * q] = b1[q]; p1[4 * q + 1] = fadd_s(b1[q], sl); p1[4 * q + 2] = fma2_s(sl, b1[q]); p1[4 * q + 3] = fadd_s(b1[q], sl3);
;                 }
;             }
.LBB0_414:
	s_cmp_lt_i32 s31, s4
	s_cbranch_scc1 .LBB0_427
	s_cmp_lg_u32 s31, s4
	s_cbranch_scc1 .Lattn_offdiag
	s_lshl_b32 s10, s21, 15
	s_and_b32 s22, s10, 0x18000
	v_add_u32_e32 v64, s22, v227
	v_add_u32_e32 v65, v64, v225
	ds_read_b128 v[124:127], v65
	ds_read_b128 v[116:119], v65 offset:4096
	v_add_u32_e32 v65, v64, v224
	ds_read_b128 v[120:123], v65
	ds_read_b128 v[108:111], v65 offset:4096
	v_add_u32_e32 v65, v64, v223
	v_add_u32_e32 v64, v64, v221
	ds_read_b128 v[112:115], v65
	ds_read_b128 v[100:103], v65 offset:4096
	ds_read_b128 v[104:107], v64
	ds_read_b128 v[96:99], v64 offset:4096
	s_cmp_eq_u32 s31, s4
	s_cselect_b64 s[22:23], -1, 0
	s_cmp_lg_u32 s31, s4
	s_cselect_b64 s[42:43], -1, 0
	s_and_b64 vcc, exec, s[22:23]
	s_cbranch_vccnz .Lattn_diag_zero
	s_sub_i32 s4, s31, s4
	s_lshl_b32 s4, s4, 6
	v_cvt_f32_i32_e32 v64, s4
	v_add_f32_e32 v64, v220, v64
	v_fma_f32 v64, v197, v64, v232
	v_xor_b32_e32 v80, 0x80000000, v64
	v_add_f32_e32 v64, v80, v201
	v_add_f32_e32 v84, v80, v199
	v_fma_f32 v88, v199, 2.0, v80
	v_add_f32_e32 v92, v80, v200
	v_add_f32_e32 v81, v80, v197
	v_fma_f32 v82, v197, 2.0, v80
	s_nop 0
	v_add_f32_e32 v68, v64, v199
	v_fma_f32 v72, v199, 2.0, v64
	v_add_f32_e32 v76, v64, v200
	v_add_f32_e32 v83, v80, v198
	v_add_f32_e32 v65, v64, v197
	v_fma_f32 v66, v197, 2.0, v64
	v_add_f32_e32 v67, v64, v198
	v_add_f32_e32 v85, v84, v197
	v_fma_f32 v86, v197, 2.0, v84
	v_add_f32_e32 v87, v84, v198
	s_nop 0
	v_add_f32_e32 v69, v68, v197
	v_fma_f32 v70, v197, 2.0, v68
	v_add_f32_e32 v71, v68, v198
	v_add_f32_e32 v89, v88, v197
	v_fma_f32 v90, v197, 2.0, v88
	v_add_f32_e32 v91, v88, v198
	v_add_f32_e32 v73, v72, v197
	v_fma_f32 v74, v197, 2.0, v72
	v_add_f32_e32 v75, v72, v198
	v_add_f32_e32 v93, v92, v197
	v_fma_f32 v94, v197, 2.0, v92
	v_add_f32_e32 v95, v92, v198
	v_add_f32_e32 v77, v76, v197
	v_fma_f32 v78, v197, 2.0, v76
	v_add_f32_e32 v79, v76, v198
